# as v23 plus write-through stores for the weight-copy (prep) outputs
# baseline (speedup 1.0000x reference)
.LBB0_651:
	v_add_u32_e32 v13, s16, v7
	v_cmp_gt_i32_e32 vcc, s28, v13
	s_and_saveexec_b64 s[10:11], vcc
	s_cbranch_execz .LBB0_653
	v_xor_b32_e32 v13, v8, v40
	v_lshlrev_b32_e32 v13, 4, v13
	v_and_b32_e32 v13, 0x70, v13
	v_add_u32_e32 v13, v11, v13
	ds_read_b128 v[14:17], v13
	v_add_u32_e32 v18, s16, v4
	v_ashrrev_i32_e32 v19, 31, v18
	v_lshlrev_b64 v[18:19], 12, v[18:19]
	v_lshl_add_u64 v[18:19], v[2:3], 0, v[18:19]
	s_waitcnt lgkmcnt(0)
	global_store_dwordx4 v[18:19], v[14:17], off sc1
.LBB0_653:
	s_or_b64 exec, exec, s[10:11]
	v_add3_u32 v13, v6, s16, 8
	v_cmp_gt_i32_e32 vcc, s28, v13
	s_and_saveexec_b64 s[10:11], vcc
	s_cbranch_execz .LBB0_655
	v_xor_b32_e32 v13, v9, v40
	v_lshlrev_b32_e32 v13, 4, v13
	v_and_b32_e32 v13, 0x70, v13
	v_add_u32_e32 v13, v11, v13
	ds_read_b128 v[14:17], v13 offset:1024
	v_add3_u32 v18, v4, s16, 8
	v_ashrrev_i32_e32 v19, 31, v18
	v_lshlrev_b64 v[18:19], 12, v[18:19]
	v_lshl_add_u64 v[18:19], v[2:3], 0, v[18:19]
	s_waitcnt lgkmcnt(0)
	global_store_dwordx4 v[18:19], v[14:17], off sc1
.LBB0_655:
	s_or_b64 exec, exec, s[10:11]
	v_add_u32_e32 v13, s16, v5
	v_add_u32_e32 v14, 0xfffe0010, v13
	v_cmp_gt_i32_e32 vcc, s28, v14
	s_and_saveexec_b64 s[10:11], vcc
	s_cbranch_execz .LBB0_657
	v_xor_b32_e32 v14, v10, v40
	v_lshlrev_b32_e32 v14, 4, v14
	v_and_b32_e32 v14, 0x70, v14
	v_add_u32_e32 v14, v11, v14
	ds_read_b128 v[14:17], v14 offset:2048
	v_add3_u32 v18, v4, s16, 16
	v_ashrrev_i32_e32 v19, 31, v18
	v_lshlrev_b64 v[18:19], 12, v[18:19]
	v_lshl_add_u64 v[18:19], v[2:3], 0, v[18:19]
	s_waitcnt lgkmcnt(0)
	global_store_dwordx4 v[18:19], v[14:17], off sc1
.LBB0_657:
	s_or_b64 exec, exec, s[10:11]
	v_add_u32_e32 v13, 0xfffe0018, v13
	v_cmp_gt_i32_e32 vcc, s28, v13
	s_and_saveexec_b64 s[10:11], vcc
	s_cbranch_execz .LBB0_650
	v_xor_b32_e32 v13, v12, v40
	v_lshlrev_b32_e32 v13, 4, v13
	v_and_b32_e32 v13, 0x70, v13
	v_add_u32_e32 v13, v11, v13
	ds_read_b128 v[14:17], v13 offset:3072
	v_add3_u32 v18, v4, s16, 24
	v_ashrrev_i32_e32 v19, 31, v18
	v_lshlrev_b64 v[18:19], 12, v[18:19]
	v_lshl_add_u64 v[18:19], v[2:3], 0, v[18:19]
	s_waitcnt lgkmcnt(0)
	global_store_dwordx4 v[18:19], v[14:17], off sc1
	s_branch .LBB0_650

.LBB0_849:
	v_ashrrev_i32_e32 v14, 31, v16
	v_mul_lo_u32 v17, s53, v16
	v_mul_lo_u32 v18, s52, v14
	v_mad_u64_u32 v[14:15], s[40:41], s52, v16, 0
	v_add3_u32 v15, v15, v18, v17
	v_lshl_add_u64 v[14:15], v[14:15], 1, v[6:7]
	s_waitcnt lgkmcnt(0)
	global_store_dwordx4 v[14:15], v[2:5], off sc1

.LBB0_862:
	v_ashrrev_i32_e32 v16, 31, v15
	v_mul_lo_u32 v18, s53, v15
	v_mul_lo_u32 v19, s52, v16
	v_mad_u64_u32 v[16:17], s[56:57], s52, v15, 0
	v_add3_u32 v17, v17, v19, v18
	v_lshl_add_u64 v[16:17], v[16:17], 1, v[6:7]
	s_waitcnt lgkmcnt(0)
	global_store_dwordx4 v[16:17], v[2:5], off sc1

.LBB0_874:
	v_ashrrev_i32_e32 v15, 31, v16
	v_mul_lo_u32 v18, s53, v16
	v_mul_lo_u32 v15, s52, v15
	v_mad_u64_u32 v[16:17], s[58:59], s52, v16, 0
	v_add3_u32 v17, v17, v15, v18
	v_lshl_add_u64 v[16:17], v[16:17], 1, v[6:7]
	s_waitcnt lgkmcnt(0)
	global_store_dwordx4 v[16:17], v[2:5], off sc1
